# remaining literal-zero state/accumulator init runs paired into v_mov_b64
# speedup vs baseline: 1.0067x; 1.0002x over previous
; __device__ void phase_hgrn_scan(const Ctx& p, int l, LAS unsigned char* lds) {
;     ...
;         f2 S[32];
; #pragma unroll
;         for (int k = 0; k < 32; ++k) S[k] = (f2){0.f, 0.f};
;         float cp = 1.f;
.Lhs_lb0:
	v_sub_f32_e32 v131, 1.0, v130
	v_mov_b32_e32 v132, 1.0
	s_cmp_eq_u32 s38, 4
	s_cbranch_scc1 .Lhs_init_s
	v_mov_b64_e32 v[0:1], 0
	v_mov_b64_e32 v[2:3], 0
	v_mov_b64_e32 v[4:5], 0
	v_mov_b64_e32 v[6:7], 0
	v_mov_b64_e32 v[8:9], 0
	v_mov_b64_e32 v[10:11], 0
	v_mov_b64_e32 v[12:13], 0
	v_mov_b64_e32 v[14:15], 0
	v_mov_b64_e32 v[16:17], 0
	v_mov_b64_e32 v[18:19], 0
	v_mov_b64_e32 v[20:21], 0
	v_mov_b64_e32 v[22:23], 0
	v_mov_b64_e32 v[24:25], 0
	v_mov_b64_e32 v[26:27], 0
	v_mov_b64_e32 v[28:29], 0
	v_mov_b64_e32 v[30:31], 0
	v_mov_b64_e32 v[32:33], 0
	v_mov_b64_e32 v[34:35], 0
	v_mov_b64_e32 v[36:37], 0
	v_mov_b64_e32 v[38:39], 0
	v_mov_b64_e32 v[40:41], 0
	v_mov_b64_e32 v[42:43], 0
	v_mov_b64_e32 v[44:45], 0
	v_mov_b64_e32 v[46:47], 0
	v_mov_b64_e32 v[48:49], 0
	v_mov_b64_e32 v[50:51], 0
	v_mov_b64_e32 v[52:53], 0
	v_mov_b64_e32 v[54:55], 0
	v_mov_b64_e32 v[56:57], 0
	v_mov_b64_e32 v[58:59], 0
	v_mov_b64_e32 v[60:61], 0
	v_mov_b64_e32 v[62:63], 0
	v_mov_b64_e32 v[64:65], 0
	v_mov_b64_e32 v[66:67], 0
	v_mov_b64_e32 v[68:69], 0
	v_mov_b64_e32 v[70:71], 0
	v_mov_b64_e32 v[72:73], 0
	v_mov_b64_e32 v[74:75], 0
	v_mov_b64_e32 v[76:77], 0
	v_mov_b64_e32 v[78:79], 0
	v_mov_b64_e32 v[80:81], 0
	v_mov_b64_e32 v[82:83], 0
	v_mov_b64_e32 v[84:85], 0
	v_mov_b64_e32 v[86:87], 0
	v_mov_b64_e32 v[88:89], 0
	v_mov_b64_e32 v[90:91], 0
	v_mov_b64_e32 v[92:93], 0
	v_mov_b64_e32 v[94:95], 0
	v_mov_b64_e32 v[96:97], 0
	v_mov_b64_e32 v[98:99], 0
	v_mov_b64_e32 v[100:101], 0
	v_mov_b64_e32 v[102:103], 0
	v_mov_b64_e32 v[104:105], 0
	v_mov_b64_e32 v[106:107], 0
	v_mov_b64_e32 v[108:109], 0
	v_mov_b64_e32 v[110:111], 0
	v_mov_b64_e32 v[112:113], 0
	v_mov_b64_e32 v[114:115], 0
	v_mov_b64_e32 v[116:117], 0
	v_mov_b64_e32 v[118:119], 0
	v_mov_b64_e32 v[120:121], 0
	v_mov_b64_e32 v[122:123], 0
	v_mov_b64_e32 v[124:125], 0
	v_mov_b64_e32 v[126:127], 0
	s_branch .Lhs_go

; __device__ __forceinline__ int tidx() { int t = threadIdx.x; asm volatile("" : "+v"(t)); return t; }
; __device__ __forceinline__ float bf2f(unsigned short b) { return __uint_as_float((unsigned)b << 16); }
; __device__ __forceinline__ f2 pfma(f2 a, f2 b, f2 c) { return __builtin_elementwise_fma(a, b, c); }
; template <bool ID> __device__ __forceinline__ void rwkv_scan(const bf16_t* __restrict__ R, const bf16_t* __restrict__ EW, const bf16_t* __restrict__ K, const bf16_t* __restrict__ V, ...
;     unsigned short q1[6], q2[6];
;     { unsigned o = base; q1[0] = R[o]; q1[1] = EW[o]; q1[2] = K[o]; q1[3] = V[o]; q1[4] = A[o]; q1[5] = B[o];
;       o = base + 512u; q2[0] = R[o]; q2[1] = EW[o]; q2[2] = K[o]; q2[3] = V[o]; q2[4] = A[o]; q2[5] = B[o]; }
;     const LAS f32x4* pa = (const LAS f32x4*)L;
;     float sav, sai;
;     { L[lane] = bf2f(q1[4]);
;       f2 av = {0.f, 0.f}, ai = {0.f, 0.f};
; #pragma unroll
;       for (int q = 0; q < 16; ++q) { const f32x4 a4 = pa[q]; const f2 a01 = {a4[0], a4[1]}, a23 = {a4[2], a4[3]};
;           av = pfma(Sv[2 * q], a01, av); av = pfma(Sv[2 * q + 1], a23, av); if (ID) { ai = pfma(Si[2 * q], a01, ai); ai = pfma(Si[2 * q + 1], a23, ai); } }
;       sav = av[0] + av[1]; sai = ai[0] + ai[1]; }
; __device__ void phase_rwkv_scan(const Ctx& p, int l, LAS unsigned char* lds) {
;     ...
;             f2 Sv[32], Si[32]; const int li = tidx() & 63;
; #pragma unroll
;             for (int i = 0; i < 32; ++i) { Sv[i] = (f2){0.f, 0.f}; Si[i] = (f2){(2 * i == li) ? 1.f : 0.f, (2 * i + 1 == li) ? 1.f : 0.f}; }
.Lscan_v:
	v_lshrrev_b32_e32 v78, 5, v139
	v_and_b32_e32 v79, 31, v139
	s_mov_b32 s26, -1
	s_mov_b32 s27, 0
	s_lshl_b32 s14, s36, 13
	s_and_b32 s14, s14, 0xffff0000
	s_lshl_b32 s15, s36, 6
	s_and_b32 s15, s15, 0x1c0
	s_or_b32 s14, s14, s15
	v_add_lshl_u32 v72, s14, v139, 1
	v_add_lshl_u32 v81, s14, v79, 1
	v_mov_b32_e32 v74, s20
	v_mov_b32_e32 v75, s21
	v_mov_b32_e32 v80, s6
	v_cndmask_b32_e64 v74, v80, v74, s[26:27]
	v_mov_b32_e32 v80, s7
	v_cndmask_b32_e64 v75, v80, v75, s[26:27]
	v_add_co_u32_e32 v74, vcc, v74, v81
	s_nop 1
	v_addc_co_u32_e32 v75, vcc, 0, v75, vcc
	v_lshl_add_u32 v76, v78, 4, s10
	v_lshl_add_u32 v77, v139, 2, s10
	v_lshl_add_u32 v251, v79, 2, s10
	v_mov_b32_e32 v246, 1.0
	v_lshlrev_b32_e32 v81, 2, v78
	v_sub_u32_e32 v81, v79, v81
	global_load_ushort v224, v72, s[4:5] offset:0
	global_load_ushort v225, v72, s[0:1] offset:0
	global_load_ushort v226, v72, s[12:13] offset:1024
	global_load_ushort v227, v[74:75], off offset:0
	global_load_ushort v228, v[74:75], off offset:64
	global_load_ushort v229, v72, s[2:3] offset:0
	global_load_ushort v230, v72, s[4:5] offset:1024
	global_load_ushort v231, v72, s[0:1] offset:1024
	global_load_ushort v232, v72, s[12:13] offset:2048
	global_load_ushort v233, v[74:75], off offset:1024
	global_load_ushort v234, v[74:75], off offset:1088
	global_load_ushort v235, v72, s[2:3] offset:1024
	global_load_ushort v82, v72, s[4:5] offset:2048
	global_load_ushort v83, v72, s[0:1] offset:2048
	global_load_ushort v84, v72, s[12:13] offset:3072
	global_load_ushort v85, v[74:75], off offset:2048
	global_load_ushort v86, v[74:75], off offset:2112
	global_load_ushort v87, v72, s[2:3] offset:2048
	v_add_u32_e32 v72, 0xc00, v72
	v_lshl_add_u64 v[74:75], v[74:75], 0, s[54:55]
	v_lshl_add_u64 v[74:75], v[74:75], 0, s[54:55]
	v_lshl_add_u64 v[74:75], v[74:75], 0, s[54:55]
	global_load_ushort v88, v72, s[4:5] offset:0
	global_load_ushort v89, v72, s[0:1] offset:0
	global_load_ushort v90, v72, s[12:13] offset:1024
	global_load_ushort v91, v[74:75], off offset:0
	global_load_ushort v92, v[74:75], off offset:64
	global_load_ushort v93, v72, s[2:3] offset:0
	v_add_u32_e32 v72, 0x400, v72
	v_lshl_add_u64 v[74:75], v[74:75], 0, s[54:55]
	v_mov_b64_e32 v[0:1], 0
	v_mov_b64_e32 v[2:3], 0
	v_mov_b64_e32 v[4:5], 0
	v_mov_b64_e32 v[6:7], 0
	v_mov_b64_e32 v[8:9], 0
	v_mov_b64_e32 v[10:11], 0
	v_mov_b64_e32 v[12:13], 0
	v_mov_b64_e32 v[14:15], 0
	v_mov_b64_e32 v[16:17], 0
	v_mov_b64_e32 v[18:19], 0
	v_mov_b64_e32 v[20:21], 0
	v_mov_b64_e32 v[22:23], 0
	v_mov_b64_e32 v[24:25], 0
	v_mov_b64_e32 v[26:27], 0
	v_mov_b64_e32 v[28:29], 0
	v_mov_b64_e32 v[30:31], 0
	v_mov_b64_e32 v[32:33], 0
	v_mov_b64_e32 v[34:35], 0
	v_mov_b64_e32 v[36:37], 0
	v_mov_b64_e32 v[38:39], 0
	v_mov_b64_e32 v[40:41], 0
	v_mov_b64_e32 v[42:43], 0
	v_mov_b64_e32 v[44:45], 0
	v_mov_b64_e32 v[46:47], 0
	v_mov_b64_e32 v[48:49], 0
	v_mov_b64_e32 v[50:51], 0
	v_mov_b64_e32 v[52:53], 0
	v_mov_b64_e32 v[54:55], 0
	v_mov_b64_e32 v[56:57], 0
	v_mov_b64_e32 v[58:59], 0
	v_mov_b64_e32 v[60:61], 0
	v_mov_b64_e32 v[62:63], 0
	s_waitcnt vmcnt(18)
	v_lshlrev_b32_e32 v78, 16, v224
	v_mul_f32_e32 v78, 0xbfb8aa3b, v78
	v_exp_f32_e32 v78, v78
	v_lshlrev_b32_e32 v79, 16, v225
	v_lshlrev_b32_e32 v80, 16, v226
	v_mul_f32_e32 v246, v246, v78
	v_mul_f32_e32 v79, v79, v246
	v_mul_f32_e32 v80, v80, v246
	v_rcp_f32_e32 v248, v246
	s_nop 0
	ds_write2st64_b32 v77, v248, v79 offset0:0 offset1:1
	ds_write_b32 v77, v80 offset:512
	ds_read_b32 v249, v251 offset:0
	ds_read_b32 v250, v251 offset:128
	v_lshlrev_b32_e32 v240, 16, v227
	v_lshlrev_b32_e32 v241, 16, v228
	s_waitcnt lgkmcnt(0)
	v_mul_f32_e32 v240, v240, v249
	v_mul_f32_e32 v241, v241, v250
	v_mov_b32_e32 v244, 0
	v_lshlrev_b32_e32 v245, 16, v229
	s_nop 0
	s_nop 0
	v_permlane32_swap_b32_e32 v244, v245
	s_movk_i32 s41, 0

; __device__ __forceinline__ int tidx() { int t = threadIdx.x; asm volatile("" : "+v"(t)); return t; }
; __device__ __forceinline__ float bf2f(unsigned short b) { return __uint_as_float((unsigned)b << 16); }
; __device__ __forceinline__ f2 pfma(f2 a, f2 b, f2 c) { return __builtin_elementwise_fma(a, b, c); }
; template <bool ID> __device__ __forceinline__ void rwkv_scan(const bf16_t* __restrict__ R, const bf16_t* __restrict__ EW, const bf16_t* __restrict__ K, const bf16_t* __restrict__ V, ...
;     unsigned short q1[6], q2[6];
;     { unsigned o = base; q1[0] = R[o]; q1[1] = EW[o]; q1[2] = K[o]; q1[3] = V[o]; q1[4] = A[o]; q1[5] = B[o];
;       o = base + 512u; q2[0] = R[o]; q2[1] = EW[o]; q2[2] = K[o]; q2[3] = V[o]; q2[4] = A[o]; q2[5] = B[o]; }
;     const LAS f32x4* pa = (const LAS f32x4*)L;
;     float sav, sai;
;     { L[lane] = bf2f(q1[4]);
;       f2 av = {0.f, 0.f}, ai = {0.f, 0.f};
; #pragma unroll
;       for (int q = 0; q < 16; ++q) { const f32x4 a4 = pa[q]; const f2 a01 = {a4[0], a4[1]}, a23 = {a4[2], a4[3]};
;           av = pfma(Sv[2 * q], a01, av); av = pfma(Sv[2 * q + 1], a23, av); if (ID) { ai = pfma(Si[2 * q], a01, ai); ai = pfma(Si[2 * q + 1], a23, ai); } }
;       sav = av[0] + av[1]; sai = ai[0] + ai[1]; }
; __device__ void phase_rwkv_scan(const Ctx& p, int l, LAS unsigned char* lds) {
;     ...
;             f2 Sv[32], Si[32]; const int li = tidx() & 63;
; #pragma unroll
;             for (int i = 0; i < 32; ++i) { Sv[i] = (f2){0.f, 0.f}; Si[i] = (f2){(2 * i == li) ? 1.f : 0.f, (2 * i + 1 == li) ? 1.f : 0.f}; }
.Lscan_i:
	v_lshrrev_b32_e32 v78, 5, v139
	v_and_b32_e32 v79, 31, v139
	s_mov_b32 s26, -1
	s_mov_b32 s27, 0
	s_lshl_b32 s14, s36, 13
	s_and_b32 s14, s14, 0xffff0000
	s_lshl_b32 s15, s36, 6
	s_and_b32 s15, s15, 0x1c0
	s_or_b32 s14, s14, s15
	v_add_lshl_u32 v72, s14, v139, 1
	v_add_lshl_u32 v81, s14, v79, 1
	v_mov_b32_e32 v74, s20
	v_mov_b32_e32 v75, s21
	v_add_co_u32_e32 v74, vcc, v74, v81
	s_nop 1
	v_addc_co_u32_e32 v75, vcc, 0, v75, vcc
	v_lshl_add_u32 v76, v78, 4, s10
	v_lshl_add_u32 v77, v139, 2, s10
	v_lshl_add_u32 v251, v79, 2, s10
	v_mov_b32_e32 v246, 1.0
	v_lshlrev_b32_e32 v81, 2, v78
	v_sub_u32_e32 v81, v79, v81
	global_load_ushort v244, v72, s[12:13]
	global_load_ushort v224, v72, s[4:5] offset:0
	global_load_ushort v225, v72, s[0:1] offset:0
	global_load_ushort v226, v72, s[12:13] offset:1024
	global_load_ushort v227, v[74:75], off offset:0
	global_load_ushort v228, v[74:75], off offset:64
	global_load_ushort v230, v72, s[4:5] offset:1024
	global_load_ushort v231, v72, s[0:1] offset:1024
	global_load_ushort v232, v72, s[12:13] offset:2048
	global_load_ushort v233, v[74:75], off offset:1024
	global_load_ushort v234, v[74:75], off offset:1088
	global_load_ushort v82, v72, s[4:5] offset:2048
	global_load_ushort v83, v72, s[0:1] offset:2048
	global_load_ushort v84, v72, s[12:13] offset:3072
	global_load_ushort v85, v[74:75], off offset:2048
	global_load_ushort v86, v[74:75], off offset:2112
	v_add_u32_e32 v72, 0xc00, v72
	v_lshl_add_u64 v[74:75], v[74:75], 0, s[54:55]
	v_lshl_add_u64 v[74:75], v[74:75], 0, s[54:55]
	v_lshl_add_u64 v[74:75], v[74:75], 0, s[54:55]
	global_load_ushort v88, v72, s[4:5] offset:0
	global_load_ushort v89, v72, s[0:1] offset:0
	global_load_ushort v90, v72, s[12:13] offset:1024
	global_load_ushort v91, v[74:75], off offset:0
	global_load_ushort v92, v[74:75], off offset:64
	v_add_u32_e32 v72, 0x400, v72
	v_lshl_add_u64 v[74:75], v[74:75], 0, s[54:55]
	v_mov_b64_e32 v[32:33], 0
	v_mov_b64_e32 v[34:35], 0
	v_mov_b64_e32 v[36:37], 0
	v_mov_b64_e32 v[38:39], 0
	v_mov_b64_e32 v[40:41], 0
	v_mov_b64_e32 v[42:43], 0
	v_mov_b64_e32 v[44:45], 0
	v_mov_b64_e32 v[46:47], 0
	v_mov_b64_e32 v[16:17], 0
	v_mov_b64_e32 v[18:19], 0
	v_mov_b64_e32 v[20:21], 0
	v_mov_b64_e32 v[22:23], 0
	v_mov_b64_e32 v[24:25], 0
	v_mov_b64_e32 v[26:27], 0
	v_mov_b64_e32 v[28:29], 0
	v_mov_b64_e32 v[30:31], 0
	v_cmp_eq_u32_e64 s[14:15], 0, v81
	s_nop 1
	v_cndmask_b32_e64 v0, 0, 1.0, s[14:15]
	v_cndmask_b32_e64 v48, 0, 1.0, s[14:15]
	v_cmp_eq_u32_e64 s[14:15], 1, v81
	s_nop 1
	v_cndmask_b32_e64 v1, 0, 1.0, s[14:15]
	v_cndmask_b32_e64 v49, 0, 1.0, s[14:15]
	v_cmp_eq_u32_e64 s[14:15], 2, v81
	s_nop 1
	v_cndmask_b32_e64 v2, 0, 1.0, s[14:15]
	v_cndmask_b32_e64 v50, 0, 1.0, s[14:15]
	v_cmp_eq_u32_e64 s[14:15], 3, v81
	s_nop 1
	v_cndmask_b32_e64 v3, 0, 1.0, s[14:15]
	v_cndmask_b32_e64 v51, 0, 1.0, s[14:15]
	v_cmp_eq_u32_e64 s[14:15], 8, v81
	s_nop 1
	v_cndmask_b32_e64 v4, 0, 1.0, s[14:15]
	v_cndmask_b32_e64 v52, 0, 1.0, s[14:15]
	v_cmp_eq_u32_e64 s[14:15], 9, v81
	s_nop 1
	v_cndmask_b32_e64 v5, 0, 1.0, s[14:15]
	v_cndmask_b32_e64 v53, 0, 1.0, s[14:15]
	v_cmp_eq_u32_e64 s[14:15], 10, v81
	s_nop 1
	v_cndmask_b32_e64 v6, 0, 1.0, s[14:15]
	v_cndmask_b32_e64 v54, 0, 1.0, s[14:15]
	v_cmp_eq_u32_e64 s[14:15], 11, v81
	s_nop 1
	v_cndmask_b32_e64 v7, 0, 1.0, s[14:15]
	v_cndmask_b32_e64 v55, 0, 1.0, s[14:15]
	v_cmp_eq_u32_e64 s[14:15], 16, v81
	s_nop 1
	v_cndmask_b32_e64 v8, 0, 1.0, s[14:15]
	v_cndmask_b32_e64 v56, 0, 1.0, s[14:15]
	v_cmp_eq_u32_e64 s[14:15], 17, v81
	s_nop 1
	v_cndmask_b32_e64 v9, 0, 1.0, s[14:15]
	v_cndmask_b32_e64 v57, 0, 1.0, s[14:15]
	v_cmp_eq_u32_e64 s[14:15], 18, v81
	s_nop 1
	v_cndmask_b32_e64 v10, 0, 1.0, s[14:15]
	v_cndmask_b32_e64 v58, 0, 1.0, s[14:15]
	v_cmp_eq_u32_e64 s[14:15], 19, v81
	s_nop 1
	v_cndmask_b32_e64 v11, 0, 1.0, s[14:15]
	v_cndmask_b32_e64 v59, 0, 1.0, s[14:15]
	v_cmp_eq_u32_e64 s[14:15], 24, v81
	s_nop 1
	v_cndmask_b32_e64 v12, 0, 1.0, s[14:15]
	v_cndmask_b32_e64 v60, 0, 1.0, s[14:15]
	v_cmp_eq_u32_e64 s[14:15], 25, v81
	s_nop 1
	v_cndmask_b32_e64 v13, 0, 1.0, s[14:15]
	v_cndmask_b32_e64 v61, 0, 1.0, s[14:15]
	v_cmp_eq_u32_e64 s[14:15], 26, v81
	s_nop 1
	v_cndmask_b32_e64 v14, 0, 1.0, s[14:15]
	v_cndmask_b32_e64 v62, 0, 1.0, s[14:15]
	v_cmp_eq_u32_e64 s[14:15], 27, v81
	s_nop 1
	v_cndmask_b32_e64 v15, 0, 1.0, s[14:15]
	v_cndmask_b32_e64 v63, 0, 1.0, s[14:15]
	s_waitcnt vmcnt(15)
	v_lshlrev_b32_e32 v78, 16, v224
	v_mul_f32_e32 v78, 0xbfb8aa3b, v78
	v_exp_f32_e32 v78, v78
	v_lshlrev_b32_e32 v79, 16, v225
	v_lshlrev_b32_e32 v80, 16, v226
	v_mul_f32_e32 v246, v246, v78
	v_mul_f32_e32 v79, v79, v246
	v_mul_f32_e32 v80, v80, v246
	v_rcp_f32_e32 v248, v246
	s_nop 0
	ds_write2st64_b32 v77, v248, v79 offset0:0 offset1:1
	ds_write_b32 v77, v80 offset:512
	ds_read_b32 v249, v251 offset:0
	ds_read_b32 v250, v251 offset:128
	v_lshlrev_b32_e32 v240, 16, v227
	v_lshlrev_b32_e32 v241, 16, v228
	s_waitcnt lgkmcnt(0)
	v_mul_f32_e32 v240, v240, v249
	v_mul_f32_e32 v241, v241, v250
	v_lshlrev_b32_e32 v244, 16, v244
	s_movk_i32 s41, 0
